# E63: E62 plus MLA second tile copy: K fragments in v[246:253] so its end-of-QK exp2/row-sum/cvt block is re-spaced two per gap behind MFMA 9..17
# speedup vs baseline: 1.0062x; 1.0002x over previous
; #define PK4(P, BASE, OUT) do { u32x4 w = {cvtb(P[BASE + 0], P[BASE + 1]), cvtb(P[BASE + 2], P[BASE + 3]), \
;     cvtb(P[BASE + 4], P[BASE + 5]), cvtb(P[BASE + 6], P[BASE + 7])}; OUT = *reinterpret_cast<bf16x8*>(&w); } while (0)
; __device__ __forceinline__ void finishSM(f32x16& p0, f32x16& p1, float alpha, float& l_reg, bf16x8& pa0, bf16x8& pa1, bf16x8& pa2, bf16x8& pa3) {
; #pragma unroll
;   for (int r = 0; r < 16; ++r) p1[r] = __builtin_amdgcn_exp2f(p1[r]);
;   float ps = 0;
; #pragma unroll
;   for (int r = 0; r < 16; ++r) ps += p0[r];
; #pragma unroll
;   for (int r = 0; r < 16; ++r) ps += p1[r];
;   { auto rr = __builtin_amdgcn_permlane32_swap(__float_as_uint(ps), __float_as_uint(ps), false, false);
;     ps = __uint_as_float(rr[0]) + __uint_as_float(rr[1]); }
;   l_reg = l_reg * alpha + ps;
;     ...
;   PK4(p0, 0, pa0); PK4(p0, 8, pa1); PK4(p1, 0, pa2); PK4(p1, 8, pa3);
;     ...
; }
; template <int NQK>
; __device__ __forceinline__ void qkt(f32x16& p0, f32x16& p1, const char* Ks, const bf16x8* qr, int r32, int hi) {
;   constexpr int KROW = NQK * 32 + 16;
;   p0 = f32x16{}; p1 = f32x16{};
; #pragma unroll
;   for (int d0 = 0; d0 < NQK; ++d0) { const int cb = (d0 * 16 + hi * 8) * 2;
;     bf16x8 b0 = *reinterpret_cast<const bf16x8*>(Ks + r32 * KROW + cb);
;     bf16x8 b1 = *reinterpret_cast<const bf16x8*>(Ks + (32 + r32) * KROW + cb);
;     p0 = __builtin_amdgcn_mfma_f32_32x32x16_bf16(b0, qr[d0], p0, 0, 0, 0);
;     p1 = __builtin_amdgcn_mfma_f32_32x32x16_bf16(b1, qr[d0], p1, 0, 0, 0); }
; template <int D0> __device__ __forceinline__ void pv_one_sm(f32x16& od, int vb, bf16x8 pa0, bf16x8 pa1, bf16x8 pa2, bf16x8 pa3, f32x16& q0, f32x16& q1, const float C, const float mnC) {
;     ...
;   if (D0 < 2) {
; #pragma unroll
;     for (int r = 8 * D0; r < 8 * D0 + 8; ++r) q0[r] = __builtin_amdgcn_exp2f(fmaf(q0[r], C, mnC));
;   } else {
; #pragma unroll
;     for (int r = 8 * (D0 - 2); r < 8 * (D0 - 2) + 8; ++r) q1[r] = fmaf(q1[r], C, mnC);
;   }
.LBB0_2543:
	v_cndmask_b32_e64 v178, v180, v178, s[8:9]
	v_mul_f32_e32 v154, 0xbdd53b94, v178
	v_fmamk_f32 v80, v80, 0x3dd53b94, v154
	v_exp_f32_e32 v155, v80
	v_fmamk_f32 v80, v81, 0x3dd53b94, v154
	v_exp_f32_e32 v156, v80
	v_fmamk_f32 v80, v82, 0x3dd53b94, v154
	v_exp_f32_e32 v157, v80
	v_fmamk_f32 v80, v83, 0x3dd53b94, v154
	v_exp_f32_e32 v159, v80
	v_fmamk_f32 v80, v84, 0x3dd53b94, v154
	v_exp_f32_e32 v160, v80
	v_fmamk_f32 v80, v85, 0x3dd53b94, v154
	v_exp_f32_e32 v161, v80
	v_fmamk_f32 v80, v86, 0x3dd53b94, v154
	v_exp_f32_e32 v180, v80
	v_fmamk_f32 v80, v87, 0x3dd53b94, v154
	v_exp_f32_e32 v189, v80
	v_fmamk_f32 v80, v88, 0x3dd53b94, v154
	v_exp_f32_e32 v191, v80
	v_fmamk_f32 v80, v89, 0x3dd53b94, v154
	v_exp_f32_e32 v198, v80
	v_fmamk_f32 v80, v90, 0x3dd53b94, v154
	v_exp_f32_e32 v199, v80
	v_fmamk_f32 v80, v91, 0x3dd53b94, v154
	v_exp_f32_e32 v200, v80
	v_fmamk_f32 v80, v92, 0x3dd53b94, v154
	v_exp_f32_e32 v201, v80
	v_fmamk_f32 v80, v93, 0x3dd53b94, v154
	v_exp_f32_e32 v214, v80
	v_fmamk_f32 v80, v94, 0x3dd53b94, v154
	v_exp_f32_e32 v215, v80
	v_fmamk_f32 v80, v95, 0x3dd53b94, v154
	v_fmamk_f32 v184, v66, 0x3dd53b94, v154
	v_fmamk_f32 v185, v68, 0x3dd53b94, v154
	v_exp_f32_e32 v216, v80
	v_fmamk_f32 v158, v64, 0x3dd53b94, v154
	v_fmamk_f32 v217, v70, 0x3dd53b94, v154
	v_fmamk_f32 v218, v65, 0x3dd53b94, v154
	v_fmamk_f32 v219, v67, 0x3dd53b94, v154
	v_fmamk_f32 v220, v69, 0x3dd53b94, v154
	v_fmamk_f32 v221, v71, 0x3dd53b94, v154
	v_fmamk_f32 v222, v72, 0x3dd53b94, v154
	v_fmamk_f32 v223, v73, 0x3dd53b94, v154
	v_fmamk_f32 v224, v74, 0x3dd53b94, v154
	v_fmamk_f32 v225, v75, 0x3dd53b94, v154
	v_fmamk_f32 v226, v76, 0x3dd53b94, v154
	v_fmamk_f32 v227, v77, 0x3dd53b94, v154
	v_fmamk_f32 v228, v78, 0x3dd53b94, v154
	v_fmac_f32_e32 v154, 0x3dd53b94, v79
	s_waitcnt lgkmcnt(0)
	s_barrier
	v_add_u32_e32 v229, s17, v174
	ds_read_b128 v[64:67], v229 offset:61952
	ds_read_b128 v[68:71], v229 offset:49152
	ds_read_b128 v[246:249], v229 offset:49184
	ds_read_b128 v[250:253], v229 offset:61984
	s_waitcnt lgkmcnt(2)
	v_mfma_f32_32x32x16_bf16 v[80:95], v[68:71], v[140:143], 0
	v_mfma_f32_32x32x16_bf16 v[64:79], v[64:67], v[140:143], 0
	s_waitcnt lgkmcnt(1)
	v_mfma_f32_32x32x16_bf16 v[80:95], v[246:249], v[136:139], v[80:95]
	s_waitcnt lgkmcnt(0)
	v_mfma_f32_32x32x16_bf16 v[64:79], v[250:253], v[136:139], v[64:79]
	ds_read_b128 v[246:249], v229 offset:49216
	ds_read_b128 v[250:253], v229 offset:62016
	s_waitcnt lgkmcnt(1)
	v_mfma_f32_32x32x16_bf16 v[80:95], v[246:249], v[132:135], v[80:95]
	s_waitcnt lgkmcnt(0)
	v_mfma_f32_32x32x16_bf16 v[64:79], v[250:253], v[132:135], v[64:79]
	ds_read_b128 v[246:249], v229 offset:49248
	ds_read_b128 v[250:253], v229 offset:62048
	s_waitcnt lgkmcnt(1)
	v_mfma_f32_32x32x16_bf16 v[80:95], v[246:249], v[128:131], v[80:95]
	s_waitcnt lgkmcnt(0)
	v_mfma_f32_32x32x16_bf16 v[64:79], v[250:253], v[128:131], v[64:79]
	ds_read_b128 v[246:249], v229 offset:49280
	ds_read_b128 v[250:253], v229 offset:62080
	s_waitcnt lgkmcnt(1)
	v_mfma_f32_32x32x16_bf16 v[80:95], v[246:249], v[124:127], v[80:95]
	v_exp_f32_e32 v217, v217
	s_waitcnt lgkmcnt(0)
	v_mfma_f32_32x32x16_bf16 v[64:79], v[250:253], v[124:127], v[64:79]
	v_exp_f32_e32 v146, v158
	v_exp_f32_e32 v147, v218
	ds_read_b128 v[246:249], v229 offset:49312
	ds_read_b128 v[250:253], v229 offset:62112
	s_waitcnt lgkmcnt(1)
	v_mfma_f32_32x32x16_bf16 v[80:95], v[246:249], v[120:123], v[80:95]
	v_exp_f32_e32 v148, v184
	v_exp_f32_e32 v149, v219
	s_waitcnt lgkmcnt(0)
	v_mfma_f32_32x32x16_bf16 v[64:79], v[250:253], v[120:123], v[64:79]
	v_exp_f32_e32 v218, v221
	v_exp_f32_e32 v219, v222
	ds_read_b128 v[246:249], v229 offset:49344
	ds_read_b128 v[250:253], v229 offset:62144
	s_waitcnt lgkmcnt(1)
	v_mfma_f32_32x32x16_bf16 v[80:95], v[246:249], v[116:119], v[80:95]
	v_exp_f32_e32 v221, v224
	v_add_f32_e32 v150, 0, v155
	s_waitcnt lgkmcnt(0)
	v_mfma_f32_32x32x16_bf16 v[64:79], v[250:253], v[116:119], v[64:79]
	v_add_f32_e32 v150, v156, v150
	v_add_f32_e32 v150, v157, v150
	ds_read_b128 v[246:249], v229 offset:49376
	ds_read_b128 v[250:253], v229 offset:62176
	s_waitcnt lgkmcnt(1)
	v_mfma_f32_32x32x16_bf16 v[80:95], v[246:249], v[112:115], v[80:95]
	v_add_f32_e32 v150, v159, v150
	v_add_f32_e32 v150, v160, v150
	s_waitcnt lgkmcnt(0)
	v_mfma_f32_32x32x16_bf16 v[64:79], v[250:253], v[112:115], v[64:79]
	v_add_f32_e32 v150, v161, v150
	v_add_f32_e32 v150, v180, v150
	ds_read_b128 v[246:249], v229 offset:49408
	ds_read_b128 v[250:253], v229 offset:62208
	s_waitcnt lgkmcnt(1)
	v_mfma_f32_32x32x16_bf16 v[80:95], v[246:249], v[108:111], v[80:95]
	v_add_f32_e32 v150, v189, v150
	v_add_f32_e32 v150, v191, v150
	s_waitcnt lgkmcnt(0)
	v_mfma_f32_32x32x16_bf16 v[64:79], v[250:253], v[108:111], v[64:79]
	v_cvt_pk_bf16_f32 v160, v160, v161
	v_cvt_pk_bf16_f32 v161, v180, v189
	ds_read_b128 v[246:249], v229 offset:49440
	ds_read_b128 v[250:253], v229 offset:62240
	s_waitcnt lgkmcnt(1)
	v_mfma_f32_32x32x16_bf16 v[80:95], v[246:249], v[104:107], v[80:95]
	s_waitcnt lgkmcnt(0)
	v_mfma_f32_32x32x16_bf16 v[64:79], v[250:253], v[104:107], v[64:79]
	ds_read_b128 v[246:249], v229 offset:49472
	ds_read_b128 v[250:253], v229 offset:62272
	s_waitcnt lgkmcnt(1)
	v_mfma_f32_32x32x16_bf16 v[80:95], v[246:249], v[100:103], v[80:95]
	s_waitcnt lgkmcnt(0)
	v_mfma_f32_32x32x16_bf16 v[64:79], v[250:253], v[100:103], v[64:79]
	ds_read_b128 v[246:249], v229 offset:49504
	ds_read_b128 v[250:253], v229 offset:62304
	s_waitcnt lgkmcnt(1)
	v_mfma_f32_32x32x16_bf16 v[80:95], v[246:249], v[96:99], v[80:95]
	s_waitcnt lgkmcnt(0)
; #define SBAR() __builtin_amdgcn_sched_barrier(0)
; __device__ __forceinline__ void decideSM(const f32x16& p0, const f32x16& p1, float& m_reg, float& mn, float& alpha, const float C, const float thr) {
;   float pmax = p0[0];
; #pragma unroll
;   for (int r = 1; r < 16; ++r) pmax = fmaxf(pmax, p0[r]);
; #pragma unroll
;   for (int r = 0; r < 16; ++r) pmax = fmaxf(pmax, p1[r]);
;   { auto rr = __builtin_amdgcn_permlane32_swap(__float_as_uint(pmax), __float_as_uint(pmax), false, false);
;     pmax = fmaxf(__uint_as_float(rr[0]), __uint_as_float(rr[1])); }
;   if (__builtin_expect(__all(pmax - m_reg <= thr), 1)) { mn = m_reg; alpha = 1.f; }
;   else { mn = fmaxf(m_reg, pmax); alpha = __builtin_amdgcn_exp2f((m_reg - mn) * C); m_reg = mn; }
; }
; __device__ __forceinline__ void finishSM(f32x16& p0, f32x16& p1, float alpha, float& l_reg, bf16x8& pa0, bf16x8& pa1, bf16x8& pa2, bf16x8& pa3) {
; #pragma unroll
;   for (int r = 0; r < 16; ++r) p1[r] = __builtin_amdgcn_exp2f(p1[r]);
;   float ps = 0;
; #pragma unroll
;   for (int r = 0; r < 16; ++r) ps += p0[r];
; #pragma unroll
;   for (int r = 0; r < 16; ++r) ps += p1[r];
;   { auto rr = __builtin_amdgcn_permlane32_swap(__float_as_uint(ps), __float_as_uint(ps), false, false);
;     ps = __uint_as_float(rr[0]) + __uint_as_float(rr[1]); }
;   l_reg = l_reg * alpha + ps;
;     ...
;   PK4(p0, 0, pa0); PK4(p0, 8, pa1); PK4(p1, 0, pa2); PK4(p1, 8, pa3);
;     ...
; }
; template <int D0> __device__ __forceinline__ void pv_one_sm(f32x16& od, int vb, bf16x8 pa0, bf16x8 pa1, bf16x8 pa2, bf16x8 pa3, f32x16& q0, f32x16& q1, const float C, const float mnC) {
;   const s16x4 l0 = tr_read<v_rd_off(D0, 0, 0)>(vb), h0 = tr_read<v_rd_off(D0, 0, 1)>(vb), l1 = tr_read<v_rd_off(D0, 1, 0)>(vb), h1 = tr_read<v_rd_off(D0, 1, 1)>(vb);
;   const s16x4 l2 = tr_read<v_rd_off(D0, 2, 0)>(vb), h2 = tr_read<v_rd_off(D0, 2, 1)>(vb), l3 = tr_read<v_rd_off(D0, 3, 0)>(vb), h3 = tr_read<v_rd_off(D0, 3, 1)>(vb);
;   asm volatile("s_waitcnt lgkmcnt(0)" ::: "memory"); SBAR();
;     ...
;   od = __builtin_amdgcn_mfma_f32_32x32x16_bf16(pa0, PK(l0, h0), od, 0, 0, 0);
;   od = __builtin_amdgcn_mfma_f32_32x32x16_bf16(pa1, PK(l1, h1), od, 0, 0, 0);
;   od = __builtin_amdgcn_mfma_f32_32x32x16_bf16(pa2, PK(l2, h2), od, 0, 0, 0);
;   od = __builtin_amdgcn_mfma_f32_32x32x16_bf16(pa3, PK(l3, h3), od, 0, 0, 0);
	v_mfma_f32_32x32x16_bf16 v[64:79], v[250:253], v[96:99], v[64:79]
	v_max_f32_e32 v180, v81, v81
	v_max_f32_e32 v189, v80, v80
	v_add_f32_e32 v150, v198, v150
	v_max_f32_e32 v180, v189, v180
	v_add_f32_e32 v150, v199, v150
	v_max3_f32 v180, v180, v82, v83
	v_add_f32_e32 v150, v200, v150
	v_max3_f32 v180, v180, v84, v85
	v_add_f32_e32 v150, v201, v150
	v_max3_f32 v180, v180, v86, v87
	v_add_f32_e32 v150, v214, v150
	v_max3_f32 v180, v180, v88, v89
	v_add_f32_e32 v150, v215, v150
	v_max3_f32 v180, v180, v90, v91
	v_add_f32_e32 v150, v216, v150
	v_max3_f32 v180, v180, v92, v93
	v_exp_f32_e32 v152, v185
	v_add_f32_e32 v150, v146, v150
	v_max3_f32 v180, v180, v94, v95
	v_exp_f32_e32 v153, v220
	v_add_f32_e32 v150, v147, v150
	v_max3_f32 v180, v180, v64, v65
	v_add_f32_e32 v150, v148, v150
	v_max3_f32 v180, v180, v66, v67
	v_add_f32_e32 v150, v149, v150
	v_max3_f32 v180, v180, v68, v69
	v_add_f32_e32 v150, v152, v150
	v_max3_f32 v180, v180, v70, v71
	v_exp_f32_e32 v220, v223
	v_add_f32_e32 v150, v153, v150
	v_max3_f32 v180, v180, v72, v73
	v_add_f32_e32 v150, v217, v150
	v_max3_f32 v180, v180, v74, v75
	v_exp_f32_e32 v222, v225
	v_add_f32_e32 v150, v218, v150
	v_max3_f32 v180, v180, v76, v77
	v_exp_f32_e32 v223, v226
	v_add_f32_e32 v150, v219, v150
	v_max3_f32 v180, v180, v78, v79
	v_exp_f32_e32 v224, v227
	v_add_f32_e32 v150, v220, v150
	v_mov_b32_e32 v189, v180
	v_exp_f32_e32 v225, v228
	v_add_f32_e32 v150, v221, v150
	v_permlane32_swap_b32_e32 v180, v189
	v_exp_f32_e32 v226, v154
	v_add_f32_e32 v150, v222, v150
	v_max_f32_e32 v189, v189, v189
	v_max_f32_e32 v180, v180, v180
	v_add_f32_e32 v150, v223, v150
	v_max_f32_e32 v180, v180, v189
	v_add_f32_e32 v150, v224, v150
	v_sub_f32_e32 v189, v180, v178
	v_add_f32_e32 v150, v225, v150
	v_cmp_ge_f32_e32 vcc, s56, v189
	v_max_f32_e32 v189, v178, v178
	v_add_f32_e32 v184, v226, v150
	v_max_f32_e32 v189, v189, v180
	v_mov_b32_e32 v185, v184
	s_cmp_eq_u64 vcc, exec
	v_sub_f32_e32 v180, v178, v189
	v_permlane32_swap_b32_e32 v184, v185
	s_cselect_b64 s[8:9], -1, 0
	v_mul_f32_e32 v180, 0x3dd53b94, v180
	v_cvt_pk_bf16_f32 v158, v155, v156
	v_cvt_pk_bf16_f32 v159, v157, v159
	v_cvt_pk_bf16_f32 v154, v191, v198
	v_cvt_pk_bf16_f32 v155, v199, v200
	v_cvt_pk_bf16_f32 v156, v201, v214
	v_cvt_pk_bf16_f32 v157, v215, v216
	v_cvt_pk_bf16_f32 v150, v146, v147
	v_cvt_pk_bf16_f32 v151, v148, v149
	v_cvt_pk_bf16_f32 v152, v152, v153
	v_cvt_pk_bf16_f32 v153, v217, v218
	v_cvt_pk_bf16_f32 v146, v219, v220
	v_cvt_pk_bf16_f32 v147, v221, v222
	v_cvt_pk_bf16_f32 v148, v223, v224
	v_cvt_pk_bf16_f32 v149, v225, v226
	s_add_i32 s10, s13, 0xffff8000
	s_add_i32 s11, s12, 0x18000
	s_mov_b32 s38, s30
	s_mov_b32 s39, s31
	buffer_load_dwordx4 v[198:201], v170, s[28:31], s10 offen
	buffer_load_dwordx4 v[214:217], v170, s[28:31], s13 offen
	buffer_load_dwordx4 v[218:221], v171, s[36:39], s11 offen
	buffer_load_dwordx4 v[222:225], v176, s[36:39], s11 offen
	buffer_load_dwordx4 v[226:229], v177, s[36:39], s11 offen
	v_exp_f32_e32 v180, v180
	v_lshl_add_u32 v191, s14, 14, v168
	ds_read_b64_tr_b16 v[230:231], v191 offset:0
	ds_read_b64_tr_b16 v[232:233], v191 offset:0x800
	ds_read_b64_tr_b16 v[234:235], v191 offset:0x1000
	ds_read_b64_tr_b16 v[236:237], v191 offset:0x1800
	ds_read_b64_tr_b16 v[238:239], v191 offset:0x2000
	ds_read_b64_tr_b16 v[240:241], v191 offset:0x2800
	ds_read_b64_tr_b16 v[242:243], v191 offset:0x3000
	ds_read_b64_tr_b16 v[244:245], v191 offset:0x3800
	s_waitcnt lgkmcnt(6)
	s_nop 0
	v_mfma_f32_32x32x16_bf16 v[0:15], v[158:161], v[230:233], v[0:15]
	ds_read_b64_tr_b16 v[230:231], v191 offset:0x200
	ds_read_b64_tr_b16 v[232:233], v191 offset:0xa00
	s_waitcnt lgkmcnt(6)
	v_mfma_f32_32x32x16_bf16 v[0:15], v[154:157], v[234:237], v[0:15]
	ds_read_b64_tr_b16 v[234:235], v191 offset:0x1200
	ds_read_b64_tr_b16 v[236:237], v191 offset:0x1a00
	s_waitcnt lgkmcnt(6)
	v_mfma_f32_32x32x16_bf16 v[0:15], v[150:153], v[238:241], v[0:15]
	ds_read_b64_tr_b16 v[238:239], v191 offset:0x2200
	ds_read_b64_tr_b16 v[240:241], v191 offset:0x2a00
	s_waitcnt lgkmcnt(6)
	v_mfma_f32_32x32x16_bf16 v[0:15], v[146:149], v[242:245], v[0:15]
	ds_read_b64_tr_b16 v[242:243], v191 offset:0x3200
	ds_read_b64_tr_b16 v[244:245], v191 offset:0x3a00
	s_waitcnt lgkmcnt(6)
	v_mfma_f32_32x32x16_bf16 v[48:63], v[158:161], v[230:233], v[48:63]
	ds_read_b64_tr_b16 v[230:231], v191 offset:0x400
	ds_read_b64_tr_b16 v[232:233], v191 offset:0xc00
	s_waitcnt lgkmcnt(6)
	v_mfma_f32_32x32x16_bf16 v[48:63], v[154:157], v[234:237], v[48:63]
	ds_read_b64_tr_b16 v[234:235], v191 offset:0x1400
	ds_read_b64_tr_b16 v[236:237], v191 offset:0x1c00
	s_waitcnt lgkmcnt(6)
	v_mfma_f32_32x32x16_bf16 v[48:63], v[150:153], v[238:241], v[48:63]
	ds_read_b64_tr_b16 v[238:239], v191 offset:0x2400
	ds_read_b64_tr_b16 v[240:241], v191 offset:0x2c00
	s_waitcnt lgkmcnt(6)
	v_mfma_f32_32x32x16_bf16 v[48:63], v[146:149], v[242:245], v[48:63]
	ds_read_b64_tr_b16 v[242:243], v191 offset:0x3400
	ds_read_b64_tr_b16 v[244:245], v191 offset:0x3c00
	s_waitcnt lgkmcnt(6)
	v_mfma_f32_32x32x16_bf16 v[32:47], v[158:161], v[230:233], v[32:47]
	ds_read_b64_tr_b16 v[230:231], v191 offset:0x600
	ds_read_b64_tr_b16 v[232:233], v191 offset:0xe00
	s_waitcnt lgkmcnt(6)
	v_mfma_f32_32x32x16_bf16 v[32:47], v[154:157], v[234:237], v[32:47]
	ds_read_b64_tr_b16 v[234:235], v191 offset:0x1600
	ds_read_b64_tr_b16 v[236:237], v191 offset:0x1e00
	s_waitcnt lgkmcnt(6)
	v_mfma_f32_32x32x16_bf16 v[32:47], v[150:153], v[238:241], v[32:47]
	ds_read_b64_tr_b16 v[238:239], v191 offset:0x2600
	ds_read_b64_tr_b16 v[240:241], v191 offset:0x2e00
	s_waitcnt lgkmcnt(6)
	v_mfma_f32_32x32x16_bf16 v[32:47], v[146:149], v[242:245], v[32:47]
	ds_read_b64_tr_b16 v[242:243], v191 offset:0x3600
	ds_read_b64_tr_b16 v[244:245], v191 offset:0x3e00
	s_waitcnt lgkmcnt(0)
	v_mfma_f32_32x32x16_bf16 v[16:31], v[158:161], v[230:233], v[16:31]
	s_waitcnt vmcnt(0)
	v_cndmask_b32_e64 v180, v180, 1.0, s[8:9]
	v_cmp_gt_f32_e32 vcc, 1.0, v180
	v_mfma_f32_32x32x16_bf16 v[16:31], v[154:157], v[234:237], v[16:31]
	v_add_u32_e32 v154, s16, v175
	s_mul_i32 s16, s44, 0x6400
	s_waitcnt vmcnt(4)
	ds_write_b128 v154, v[198:201]
	s_waitcnt vmcnt(3)
	ds_write_b128 v154, v[214:217] offset:8192
	v_mfma_f32_32x32x16_bf16 v[16:31], v[150:153], v[238:241], v[16:31]
	v_add_u32_e32 v150, s16, v173
	s_waitcnt vmcnt(2)
	ds_write_b128 v150, v[218:221] offset:49152
	s_waitcnt vmcnt(1)
	ds_write_b128 v150, v[222:225] offset:49280
	s_waitcnt vmcnt(0)
	ds_write_b128 v150, v[226:229] offset:49408
	v_mfma_f32_32x32x16_bf16 v[16:31], v[146:149], v[242:245], v[16:31]
	s_cbranch_vccz .LBB0_2547
	s_and_saveexec_b64 s[10:11], s[6:7]
	ds_write_b32 v166, v180 offset:128
	s_or_b64 exec, exec, s[10:11]
	s_waitcnt lgkmcnt(0)
	v_add_u32_e32 v158, v165, v162
	ds_read_b128 v[146:149], v158 offset:224
	ds_read_b128 v[150:153], v158 offset:192
	ds_read_b128 v[154:157], v158 offset:160
	ds_read_b128 v[158:161], v158 offset:128
	s_waitcnt lgkmcnt(3)
	v_pk_mul_f32 v[12:13], v[12:13], v[146:147]
	s_waitcnt lgkmcnt(2)
	v_pk_mul_f32 v[8:9], v[8:9], v[150:151]
	s_waitcnt lgkmcnt(1)
	v_pk_mul_f32 v[4:5], v[4:5], v[154:155]
	v_pk_mul_f32 v[14:15], v[14:15], v[148:149]
	v_pk_mul_f32 v[10:11], v[10:11], v[152:153]
	v_pk_mul_f32 v[6:7], v[6:7], v[156:157]
	s_waitcnt lgkmcnt(0)
	v_pk_mul_f32 v[2:3], v[2:3], v[160:161]
	v_pk_mul_f32 v[0:1], v[0:1], v[158:159]
	v_pk_mul_f32 v[60:61], v[60:61], v[146:147]
	v_pk_mul_f32 v[56:57], v[56:57], v[150:151]
	v_pk_mul_f32 v[52:53], v[52:53], v[154:155]
	v_pk_mul_f32 v[62:63], v[62:63], v[148:149]
	v_pk_mul_f32 v[58:59], v[58:59], v[152:153]
	v_pk_mul_f32 v[54:55], v[54:55], v[156:157]
	v_pk_mul_f32 v[50:51], v[50:51], v[160:161]
	v_pk_mul_f32 v[48:49], v[48:49], v[158:159]
	v_pk_mul_f32 v[44:45], v[44:45], v[146:147]
	v_pk_mul_f32 v[40:41], v[40:41], v[150:151]
	v_pk_mul_f32 v[36:37], v[36:37], v[154:155]
	v_pk_mul_f32 v[46:47], v[46:47], v[148:149]
	v_pk_mul_f32 v[42:43], v[42:43], v[152:153]
	v_pk_mul_f32 v[38:39], v[38:39], v[156:157]
	v_pk_mul_f32 v[34:35], v[34:35], v[160:161]
	v_pk_mul_f32 v[32:33], v[32:33], v[158:159]
	v_pk_mul_f32 v[28:29], v[28:29], v[146:147]
	v_pk_mul_f32 v[24:25], v[24:25], v[150:151]
	v_pk_mul_f32 v[20:21], v[20:21], v[154:155]
	v_pk_mul_f32 v[30:31], v[30:31], v[148:149]
	v_pk_mul_f32 v[26:27], v[26:27], v[152:153]
	v_pk_mul_f32 v[22:23], v[22:23], v[156:157]
	v_pk_mul_f32 v[18:19], v[18:19], v[160:161]
	v_pk_mul_f32 v[16:17], v[16:17], v[158:159]
